# NSA selected-branch finalisation: all 10 loads and 18 LDS reads requested up front with counted waits (was 8 serialized load-update-store round trips)
# baseline (speedup 1.0000x reference)
.LBB0_1211:
	v_add_u32_e32 v0, 0x1d000, v224
	s_waitcnt lgkmcnt(0)
	s_barrier
	s_waitcnt vmcnt(0)
	ds_read_b32 v5, v0
	v_add_u32_e32 v118, 0x1d000, v223
	ds_read_b32 v118, v118
	v_lshlrev_b32_e32 v0, 1, v180
	v_lshl_add_u64 v[2:3], s[88:89], 0, v[0:1]
	v_mov_b32_e32 v0, 0
	v_lshl_add_u64 v[100:101], v[2:3], 0, v[178:179]
	v_lshl_add_u64 v[102:103], v[2:3], 0, v[176:177]
	s_mov_b64 s[6:7], 0x4502
	v_lshl_add_u64 v[6:7], v[100:101], 0, s[6:7]
	v_lshl_add_u64 v[8:9], v[102:103], 0, s[6:7]
	global_load_ushort v116, v[6:7], off
	global_load_ushort v117, v[8:9], off
	global_load_dwordx2 v[20:21], v[168:169], off
	global_load_dwordx2 v[22:23], v[168:169], off offset:32
	global_load_dwordx2 v[24:25], v[168:169], off offset:64
	global_load_dwordx2 v[26:27], v[168:169], off offset:96
	global_load_dwordx2 v[28:29], v[166:167], off
	global_load_dwordx2 v[30:31], v[166:167], off offset:32
	global_load_dwordx2 v[32:33], v[166:167], off offset:64
	global_load_dwordx2 v[34:35], v[166:167], off offset:96
	v_lshl_add_u32 v119, v220, 2, 0
	v_add_u32_e32 v8, v119, v225
	v_add_u32_e32 v14, 0xc000, v8
	v_add_u32_e32 v10, v119, v171
	v_add_u32_e32 v10, 0xc000, v10
	ds_read2_b32 v[120:121], v14 offset1:4
	ds_read2_b32 v[122:123], v14 offset0:8 offset1:12
	ds_read2_b32 v[124:125], v14 offset0:16 offset1:20
	ds_read2_b32 v[126:127], v14 offset0:24 offset1:28
	ds_read2_b32 v[128:129], v14 offset0:32 offset1:36
	ds_read2_b32 v[130:131], v14 offset0:40 offset1:44
	ds_read2_b32 v[132:133], v14 offset0:48 offset1:52
	ds_read2_b32 v[134:135], v14 offset0:56 offset1:60
	ds_read2_b32 v[72:73], v10 offset1:4
	ds_read2_b32 v[74:75], v10 offset0:8 offset1:12
	ds_read2_b32 v[76:77], v10 offset0:16 offset1:20
	ds_read2_b32 v[78:79], v10 offset0:24 offset1:28
	ds_read2_b32 v[80:81], v10 offset0:32 offset1:36
	ds_read2_b32 v[82:83], v10 offset0:40 offset1:44
	ds_read2_b32 v[84:85], v10 offset0:48 offset1:52
	ds_read2_b32 v[86:87], v10 offset0:56 offset1:60
	v_mov_b32_e32 v4, 0
	s_waitcnt lgkmcnt(0)
	v_cmp_lt_i32_e32 vcc, 0, v5
	s_and_saveexec_b64 s[28:29], vcc
	s_cbranch_execz .Lselfin_a
	v_cvt_f32_u32_e32 v5, v5
	s_waitcnt vmcnt(9)
	v_lshlrev_b32_e32 v4, 16, v116
	v_mul_f32_e32 v4, 0xbfb8aa3b, v4
	v_exp_f32_e32 v4, v4
	s_nop 0
	v_add_f32_e32 v4, 1.0, v4
	v_rcp_f32_e32 v4, v4
	s_nop 0
	v_div_scale_f32 v6, s[6:7], v5, v5, v4
	v_rcp_f32_e32 v7, v6
	v_div_scale_f32 v8, vcc, v4, v5, v4
	v_fma_f32 v9, -v6, v7, 1.0
	v_fmac_f32_e32 v7, v9, v7
	v_mul_f32_e32 v9, v8, v7
	v_fma_f32 v11, -v6, v9, v8
	v_fmac_f32_e32 v9, v11, v7
	v_fma_f32 v6, -v6, v9, v8
	v_div_fmas_f32 v6, v6, v7, v9
	v_div_fixup_f32 v4, v6, v5, v4
.Lselfin_a:
	s_or_b64 exec, exec, s[28:29]
	s_lshl_b32 s6, s68, 6
	s_lshl_b64 s[28:29], s[68:69], 20
	v_cvt_f32_i32_e32 v121, v121
	v_cvt_f32_i32_e32 v120, v120
	v_cvt_f32_i32_e32 v123, v123
	v_cvt_f32_i32_e32 v122, v122
	s_waitcnt vmcnt(7)
	v_lshlrev_b32_e32 v12, 16, v20
	v_and_b32_e32 v13, 0xffff0000, v20
	v_pk_fma_f32 v[120:121], v[4:5], v[120:121], v[12:13] op_sel_hi:[0,1,1]
	v_cvt_pk_bf16_f32 v20, v120, v121
	v_lshlrev_b32_e32 v12, 16, v21
	v_and_b32_e32 v13, 0xffff0000, v21
	v_pk_fma_f32 v[122:123], v[4:5], v[122:123], v[12:13] op_sel_hi:[0,1,1]
	v_cvt_pk_bf16_f32 v21, v122, v123
	global_store_dwordx2 v[168:169], v[20:21], off
	v_cvt_f32_i32_e32 v125, v125
	v_cvt_f32_i32_e32 v124, v124
	v_cvt_f32_i32_e32 v127, v127
	v_cvt_f32_i32_e32 v126, v126
	s_waitcnt vmcnt(7)
	v_lshlrev_b32_e32 v12, 16, v22
	v_and_b32_e32 v13, 0xffff0000, v22
	v_pk_fma_f32 v[124:125], v[4:5], v[124:125], v[12:13] op_sel_hi:[0,1,1]
	v_cvt_pk_bf16_f32 v22, v124, v125
	v_lshlrev_b32_e32 v12, 16, v23
	v_and_b32_e32 v13, 0xffff0000, v23
	v_pk_fma_f32 v[126:127], v[4:5], v[126:127], v[12:13] op_sel_hi:[0,1,1]
	v_cvt_pk_bf16_f32 v23, v126, v127
	global_store_dwordx2 v[168:169], v[22:23], off offset:32
	v_cvt_f32_i32_e32 v129, v129
	v_cvt_f32_i32_e32 v128, v128
	v_cvt_f32_i32_e32 v131, v131
	v_cvt_f32_i32_e32 v130, v130
	s_waitcnt vmcnt(7)
	v_lshlrev_b32_e32 v12, 16, v24
	v_and_b32_e32 v13, 0xffff0000, v24
	v_pk_fma_f32 v[128:129], v[4:5], v[128:129], v[12:13] op_sel_hi:[0,1,1]
	v_cvt_pk_bf16_f32 v24, v128, v129
	v_lshlrev_b32_e32 v12, 16, v25
	v_and_b32_e32 v13, 0xffff0000, v25
	v_pk_fma_f32 v[130:131], v[4:5], v[130:131], v[12:13] op_sel_hi:[0,1,1]
	v_cvt_pk_bf16_f32 v25, v130, v131
	global_store_dwordx2 v[168:169], v[24:25], off offset:64
	v_cvt_f32_i32_e32 v133, v133
	v_cvt_f32_i32_e32 v132, v132
	v_cvt_f32_i32_e32 v135, v135
	v_cvt_f32_i32_e32 v134, v134
	s_waitcnt vmcnt(7)
	v_lshlrev_b32_e32 v12, 16, v26
	v_and_b32_e32 v13, 0xffff0000, v26
	v_pk_fma_f32 v[132:133], v[4:5], v[132:133], v[12:13] op_sel_hi:[0,1,1]
	v_cvt_pk_bf16_f32 v26, v132, v133
	v_lshlrev_b32_e32 v12, 16, v27
	v_and_b32_e32 v13, 0xffff0000, v27
	v_pk_fma_f32 v[134:135], v[4:5], v[134:135], v[12:13] op_sel_hi:[0,1,1]
	v_cvt_pk_bf16_f32 v27, v134, v135
	global_store_dwordx2 v[168:169], v[26:27], off offset:96
	v_cmp_lt_i32_e32 vcc, 0, v118
	s_and_saveexec_b64 s[30:31], vcc
	s_cbranch_execz .Lselfin_b
	v_cvt_f32_u32_e32 v2, v118
	v_lshlrev_b32_e32 v0, 16, v117
	v_mul_f32_e32 v0, 0xbfb8aa3b, v0
	v_exp_f32_e32 v0, v0
	s_nop 0
	v_add_f32_e32 v0, 1.0, v0
	v_rcp_f32_e32 v0, v0
	s_nop 0
	v_div_scale_f32 v3, s[10:11], v2, v2, v0
	v_rcp_f32_e32 v4, v3
	v_div_scale_f32 v6, vcc, v0, v2, v0
	v_fma_f32 v7, -v3, v4, 1.0
	v_fmac_f32_e32 v4, v7, v4
	v_mul_f32_e32 v7, v6, v4
	v_fma_f32 v8, -v3, v7, v6
	v_fmac_f32_e32 v7, v8, v4
	v_fma_f32 v3, -v3, v7, v6
	v_div_fmas_f32 v3, v3, v4, v7
	v_div_fixup_f32 v0, v3, v2, v0
.Lselfin_b:
	s_or_b64 exec, exec, s[30:31]
	s_max_i32 s7, s27, 0x1ff
	s_add_i32 s30, s7, 0xfffffe01
	s_lshr_b32 s27, s30, 6
	s_lshl_b32 s6, s6, 1
	v_readlane_b32 s7, v249, 36
	s_add_u32 s34, s7, s6
	v_readlane_b32 s6, v249, 30
	s_addc_u32 s35, s6, 0
	s_lshl_b64 s[6:7], s[28:29], 1
	v_readlane_b32 s10, v249, 31
	s_add_u32 s6, s10, s6
	v_readlane_b32 s10, v249, 27
	s_addc_u32 s7, s10, s7
	v_cvt_f32_i32_e32 v73, v73
	v_cvt_f32_i32_e32 v72, v72
	v_cvt_f32_i32_e32 v75, v75
	v_cvt_f32_i32_e32 v74, v74
	s_waitcnt vmcnt(7)
	v_lshlrev_b32_e32 v12, 16, v28
	v_and_b32_e32 v13, 0xffff0000, v28
	v_pk_fma_f32 v[72:73], v[0:1], v[72:73], v[12:13] op_sel_hi:[0,1,1]
	v_cvt_pk_bf16_f32 v28, v72, v73
	v_lshlrev_b32_e32 v12, 16, v29
	v_and_b32_e32 v13, 0xffff0000, v29
	v_pk_fma_f32 v[74:75], v[0:1], v[74:75], v[12:13] op_sel_hi:[0,1,1]
	v_cvt_pk_bf16_f32 v29, v74, v75
	global_store_dwordx2 v[166:167], v[28:29], off
	v_cvt_f32_i32_e32 v77, v77
	v_cvt_f32_i32_e32 v76, v76
	v_cvt_f32_i32_e32 v79, v79
	v_cvt_f32_i32_e32 v78, v78
	s_waitcnt vmcnt(7)
	v_lshlrev_b32_e32 v12, 16, v30
	v_and_b32_e32 v13, 0xffff0000, v30
	v_pk_fma_f32 v[76:77], v[0:1], v[76:77], v[12:13] op_sel_hi:[0,1,1]
	v_cvt_pk_bf16_f32 v30, v76, v77
	v_lshlrev_b32_e32 v12, 16, v31
	v_and_b32_e32 v13, 0xffff0000, v31
	v_pk_fma_f32 v[78:79], v[0:1], v[78:79], v[12:13] op_sel_hi:[0,1,1]
	v_cvt_pk_bf16_f32 v31, v78, v79
	global_store_dwordx2 v[166:167], v[30:31], off offset:32
	v_cvt_f32_i32_e32 v81, v81
	v_cvt_f32_i32_e32 v80, v80
	v_cvt_f32_i32_e32 v83, v83
	v_cvt_f32_i32_e32 v82, v82
	s_waitcnt vmcnt(7)
	v_lshlrev_b32_e32 v12, 16, v32
	v_and_b32_e32 v13, 0xffff0000, v32
	v_pk_fma_f32 v[80:81], v[0:1], v[80:81], v[12:13] op_sel_hi:[0,1,1]
	v_cvt_pk_bf16_f32 v32, v80, v81
	v_lshlrev_b32_e32 v12, 16, v33
	v_and_b32_e32 v13, 0xffff0000, v33
	v_pk_fma_f32 v[82:83], v[0:1], v[82:83], v[12:13] op_sel_hi:[0,1,1]
	v_cvt_pk_bf16_f32 v33, v82, v83
	global_store_dwordx2 v[166:167], v[32:33], off offset:64
	v_cvt_f32_i32_e32 v85, v85
	v_cvt_f32_i32_e32 v84, v84
	v_cvt_f32_i32_e32 v87, v87
	v_cvt_f32_i32_e32 v86, v86
	s_waitcnt vmcnt(7)
	v_lshlrev_b32_e32 v12, 16, v34
	v_and_b32_e32 v13, 0xffff0000, v34
	v_pk_fma_f32 v[84:85], v[0:1], v[84:85], v[12:13] op_sel_hi:[0,1,1]
	v_cvt_pk_bf16_f32 v34, v84, v85
	v_lshlrev_b32_e32 v12, 16, v35
	v_and_b32_e32 v13, 0xffff0000, v35
	v_pk_fma_f32 v[86:87], v[0:1], v[86:87], v[12:13] op_sel_hi:[0,1,1]
	v_cvt_pk_bf16_f32 v35, v86, v87
	global_store_dwordx2 v[166:167], v[34:35], off offset:96
	s_barrier
	global_load_dwordx4 v[4:7], v[172:173], off offset:3072
	global_load_dwordx4 v[8:11], v[172:173], off offset:3136
	global_load_dwordx4 v[12:15], v[174:175], off offset:3072
	global_load_dwordx4 v[16:19], v[174:175], off offset:3136
	s_nop 0
	v_ashrrev_i32_e32 v2, 3, v218
	v_and_b32_e32 v0, 7, v218
	v_lshrrev_b32_e32 v3, 4, v218
	v_lshrrev_b32_e32 v20, 3, v2
	v_readfirstlane_b32 s10, v218
	v_xor_b32_e32 v22, v3, v218
	v_bfe_u32 v3, v2, 1, 3
	v_bitop3_b32 v0, v20, v0, 2 bitop3:0x6c
	s_lshl_b32 s10, s10, 4
	v_xor_b32_e32 v23, v0, v3
	s_and_b32 s50, s10, 0xfffffc00
	v_ashrrev_i32_e32 v3, 31, v2
	s_add_i32 s50, s50, 0
	v_lshlrev_b64 v[20:21], 15, v[2:3]
	v_lshlrev_b32_e32 v0, 4, v22
	v_lshl_add_u64 v[20:21], s[6:7], 0, v[20:21]
	v_and_b32_e32 v0, 0x70, v0
	s_cmp_le_u32 s27, s25
	v_lshl_add_u64 v[20:21], v[20:21], 0, v[0:1]
	s_cselect_b64 s[28:29], -1, 0
	s_cmp_gt_u32 s27, s25
	v_lshlrev_b32_e32 v0, 4, v23
	s_cbranch_scc1 .LBB0_1251
	s_and_b32 s68, s30, 0xffffffc0
	v_add_u32_e32 v3, s68, v2
	v_min_i32_e32 v3, 0x3fff, v3
	v_mov_b64_e32 v[22:23], s[34:35]
	v_mad_i64_i32 v[22:23], s[6:7], v3, s63, v[22:23]
	v_lshl_add_u64 v[22:23], v[22:23], 0, v[0:1]
	s_mov_b32 s6, m0
	s_mov_b32 m0, s50
	s_nop 0
	global_load_lds_dwordx4 v[22:23], off
	s_mov_b32 m0, s6
	v_lshl_add_u64 v[22:23], s[68:69], 1, v[20:21]
	s_add_i32 s6, s50, 0x2000
	s_mov_b32 s7, m0
	s_mov_b32 m0, s6
	s_nop 0
	global_load_lds_dwordx4 v[22:23], off
	s_mov_b32 m0, s7
	s_add_i32 s54, s27, 1
	s_cmp_ge_u32 s27, s25
	s_cbranch_scc0 .LBB0_1252
